# v74 + next-tile coordinates in the phase 1/3/9 tile loops computed incrementally (col+4, same panel) when the grid is 256, skipping the ~50-instruction division block per tile
# baseline (speedup 1.0000x reference)
.LBB0_134:
	s_add_i32 s36, s36, 1
	s_mul_i32 s2, s36, s44
	s_mul_hi_u32 s3, s36, s45
	s_add_i32 s3, s3, s2
	s_mul_i32 s2, s36, s45
	s_add_u32 s2, s2, s84
	s_addc_u32 s3, s3, s29
	v_cmp_gt_i64_e32 vcc, s[2:3], v[160:161]
	v_cmp_lt_i64_e64 s[4:5], s[2:3], v[158:159]
	s_cbranch_vccnz .LBB0_136
	s_cmp_eq_u32 s45, 0x100
	s_cbranch_scc0 .Lidx_slow_134
	s_cmp_eq_u32 s44, 0
	s_cbranch_scc0 .Lidx_slow_134
	s_add_i32 s48, s51, 4
	s_mov_b32 s49, s50
	s_branch .LBB0_136
.Lidx_slow_134:
	s_ashr_i32 s3, s2, 31
	s_lshr_b32 s3, s3, 29
	s_add_i32 s3, s2, s3
	s_ashr_i32 s18, s3, 3
	s_and_b32 s3, s3, -8
	s_sub_i32 s2, s2, s3
	s_cmp_lt_i32 s2, 0
	s_cselect_b32 s3, s30, 0x160
	s_mul_i32 s2, s2, s3
	s_add_i32 s2, s2, s18
	s_mul_hi_i32 s3, s2, 0x2e8ba2e9
	s_lshr_b32 s18, s3, 31
	s_ashr_i32 s3, s3, 6
	s_add_i32 s3, s3, s18
	s_lshl_b32 s18, s3, 3
	s_sub_i32 s19, 64, s18
	s_min_i32 s19, s19, 8
	s_abs_i32 s48, s19
	v_cvt_f32_u32_e32 v0, s48
	s_sub_i32 s52, 0, s48
	s_mulk_i32 s3, 0x160
	s_sub_i32 s2, s2, s3
	v_rcp_iflag_f32_e32 v0, v0
	s_abs_i32 s3, s2
	s_xor_b32 s49, s2, s19
	s_ashr_i32 s49, s49, 31
	v_mul_f32_e32 v0, 0x4f7ffffe, v0
	v_cvt_u32_f32_e32 v0, v0
	s_nop 0
	v_readfirstlane_b32 s53, v0
	s_mul_i32 s52, s52, s53
	s_mul_hi_u32 s52, s53, s52
	s_add_i32 s53, s53, s52
	s_mul_hi_u32 s52, s3, s53
	s_mul_i32 s53, s52, s48
	s_sub_i32 s3, s3, s53
	s_add_i32 s54, s52, 1
	s_sub_i32 s53, s3, s48
	s_cmp_ge_u32 s3, s48
	s_cselect_b32 s52, s54, s52
	s_cselect_b32 s3, s53, s3
	s_add_i32 s53, s52, 1
	s_cmp_ge_u32 s3, s48
	s_cselect_b32 s3, s53, s52
	s_xor_b32 s3, s3, s49
	s_sub_i32 s48, s3, s49
	s_mul_i32 s3, s48, s19
	s_sub_i32 s2, s2, s3
	s_add_i32 s49, s18, s2

.LBB0_315:
	s_add_i32 s86, s86, 1
	s_mul_i32 s0, s86, s79
	s_mul_hi_u32 s1, s86, s80
	s_add_i32 s1, s1, s0
	s_mul_i32 s0, s86, s80
	s_add_u32 s6, s0, s97
	s_addc_u32 s7, s1, s81
	v_cmp_gt_i64_e32 vcc, s[6:7], v[182:183]
	v_cmp_lt_i64_e64 s[0:1], s[6:7], v[180:181]
	s_cbranch_vccnz .LBB0_317
	s_cmp_eq_u32 s80, 0x100
	s_cbranch_scc0 .Lidx_slow_315
	s_cmp_eq_u32 s79, 0
	s_cbranch_scc0 .Lidx_slow_315
	s_add_i32 s87, s89, 4
	s_mov_b32 s88, s12
	s_branch .LBB0_317
.Lidx_slow_315:
	s_ashr_i32 s7, s6, 31
	s_lshr_b32 s7, s7, 29
	s_add_i32 s7, s6, s7
	s_ashr_i32 s33, s7, 3
	s_and_b32 s7, s7, -8
	s_sub_i32 s6, s6, s7
	s_cmp_lt_i32 s6, 0
	s_movk_i32 s7, 0x131
	s_cselect_b32 s7, s7, 0x130
	s_mul_i32 s6, s6, s7
	s_add_i32 s6, s6, s33
	s_mul_hi_i32 s7, s6, 0x6bca1af3
	s_lshr_b32 s33, s7, 31
	s_ashr_i32 s7, s7, 7
	s_add_i32 s7, s7, s33
	s_lshl_b32 s33, s7, 3
	s_sub_i32 s46, 64, s33
	s_min_i32 s46, s46, 8
	s_abs_i32 s47, s46
	v_cvt_f32_u32_e32 v0, s47
	s_sub_i32 s49, 0, s47
	s_mulk_i32 s7, 0x130
	s_sub_i32 s6, s6, s7
	v_rcp_iflag_f32_e32 v0, v0
	s_abs_i32 s7, s6
	s_xor_b32 s48, s6, s46
	s_ashr_i32 s48, s48, 31
	v_mul_f32_e32 v0, 0x4f7ffffe, v0
	v_cvt_u32_f32_e32 v0, v0
	s_nop 0
	v_readfirstlane_b32 s54, v0
	s_mul_i32 s49, s49, s54
	s_mul_hi_u32 s49, s54, s49
	s_add_i32 s54, s54, s49
	s_mul_hi_u32 s49, s7, s54
	s_mul_i32 s54, s49, s47
	s_sub_i32 s7, s7, s54
	s_add_i32 s55, s49, 1
	s_sub_i32 s54, s7, s47
	s_cmp_ge_u32 s7, s47
	s_cselect_b32 s49, s55, s49
	s_cselect_b32 s7, s54, s7
	s_add_i32 s54, s49, 1
	s_cmp_ge_u32 s7, s47
	s_cselect_b32 s7, s54, s49
	s_xor_b32 s7, s7, s48
	s_sub_i32 s87, s7, s48
	s_mul_i32 s7, s87, s46
	s_sub_i32 s6, s6, s7
	s_add_i32 s88, s33, s6

.LBB0_962:
	s_add_i32 s46, s46, 1
	s_mul_i32 s0, s46, s54
	s_mul_hi_u32 s1, s46, s55
	s_add_i32 s1, s1, s0
	s_mul_i32 s0, s46, s55
	s_add_u32 s0, s0, s84
	s_addc_u32 s1, s1, s40
	v_cmp_gt_i64_e32 vcc, s[0:1], v[162:163]
	v_cmp_lt_i64_e64 s[2:3], s[0:1], v[160:161]
	s_cbranch_vccnz .LBB0_964
	s_cmp_eq_u32 s55, 0x100
	s_cbranch_scc0 .Lidx_slow_962
	s_cmp_eq_u32 s54, 0
	s_cbranch_scc0 .Lidx_slow_962
	s_add_i32 s63, s66, 4
	s_mov_b32 s64, s65
	s_branch .LBB0_964
.Lidx_slow_962:
	s_ashr_i32 s1, s0, 31
	s_lshr_b32 s1, s1, 29
	s_add_i32 s1, s0, s1
	s_ashr_i32 s8, s1, 3
	s_and_b32 s1, s1, -8
	s_sub_i32 s0, s0, s1
	s_cmp_lt_i32 s0, 0
	s_cselect_b32 s1, s41, 0x160
	s_mul_i32 s0, s0, s1
	s_add_i32 s0, s0, s8
	s_mul_hi_i32 s1, s0, 0x2e8ba2e9
	s_lshr_b32 s8, s1, 31
	s_ashr_i32 s1, s1, 6
	s_add_i32 s1, s1, s8
	s_lshl_b32 s8, s1, 3
	s_sub_i32 s9, 64, s8
	s_min_i32 s9, s9, 8
	s_abs_i32 s10, s9
	v_cvt_f32_u32_e32 v0, s10
	s_sub_i32 s12, 0, s10
	s_mulk_i32 s1, 0x160
	s_sub_i32 s0, s0, s1
	v_rcp_iflag_f32_e32 v0, v0
	s_abs_i32 s1, s0
	s_xor_b32 s11, s0, s9
	s_ashr_i32 s11, s11, 31
	v_mul_f32_e32 v0, 0x4f7ffffe, v0
	v_cvt_u32_f32_e32 v0, v0
	s_nop 0
	v_readfirstlane_b32 s13, v0
	s_mul_i32 s12, s12, s13
	s_mul_hi_u32 s12, s13, s12
	s_add_i32 s13, s13, s12
	s_mul_hi_u32 s12, s1, s13
	s_mul_i32 s13, s12, s10
	s_sub_i32 s1, s1, s13
	s_add_i32 s30, s12, 1
	s_sub_i32 s13, s1, s10
	s_cmp_ge_u32 s1, s10
	s_cselect_b32 s12, s30, s12
	s_cselect_b32 s1, s13, s1
	s_add_i32 s13, s12, 1
	s_cmp_ge_u32 s1, s10
	s_cselect_b32 s1, s13, s12
	s_xor_b32 s1, s1, s11
	s_sub_i32 s63, s1, s11
	s_mul_i32 s1, s63, s9
	s_sub_i32 s0, s0, s1
	s_add_i32 s64, s8, s0
